# grid barrier: non-last workgroups poll the top-level generation word directly instead of their XCD's republished word (one hop fewer per barrier)
# baseline (speedup 1.0000x reference)
; DI unsigned xb_ld(unsigned* p) { return __hip_atomic_load(p, __ATOMIC_RELAXED, __HIP_MEMORY_SCOPE_AGENT); }
; DI unsigned xb_add(unsigned* p, unsigned v) { return __hip_atomic_fetch_add(p, v, __ATOMIC_RELAXED, __HIP_MEMORY_SCOPE_AGENT); }
; #define XB_SPIN(cond, bar) do { unsigned _sp = 0; while (cond) { __builtin_amdgcn_s_sleep(1); \
;     if ((++_sp & 255u) == 0u) { if (xb_ld(&(bar)[XB_TMO])) break; if (_sp > XB_SPIN_CAP) { atomicAdd(&(bar)[XB_TMO], 1u); break; } } } } while (0)
; DI void xcd_barrier(XcdBarrier& b) {
;     ...
;     const unsigned old = xb_add(&bar[XB_XSUB(b.x)], 1u);
;     const unsigned gen = old / nloc;
;     if (old + 1u == (gen + 1u) * nloc) {
;       __builtin_amdgcn_fence(__ATOMIC_RELEASE, "agent");
;       asm volatile("s_waitcnt vmcnt(0)" ::: "memory");
;       const unsigned og = xb_add(&bar[XB_TOP], 1u);
;       const unsigned tg = og / nx;
;       if (og + 1u == (tg + 1u) * nx) xb_add(&bar[XB_TOPGEN], 1u);
;       else XB_SPIN(xb_ld(&bar[XB_TOPGEN]) == tg, bar);
;       __builtin_amdgcn_fence(__ATOMIC_ACQUIRE, "agent");
;       xb_add(&bar[XB_XGEN(b.x)], 1u);
;       asm volatile("s_waitcnt vmcnt(0)" ::: "memory");
;     } else {
;       XB_SPIN(xb_ld(&bar[XB_XGEN(b.x)]) == gen, bar);
.LBB0_164:
	s_or_b64 exec, exec, s[4:5]
	global_atomic_add v0, v[110:111], v133, off sc0
	v_cvt_f32_u32_e32 v1, v116
	v_sub_u32_e32 v2, 0, v116
	v_rcp_iflag_f32_e32 v1, v1
	s_nop 0
	v_mul_f32_e32 v1, 0x4f7ffffe, v1
	v_cvt_u32_f32_e32 v1, v1
	v_mul_lo_u32 v2, v2, v1
	v_mul_hi_u32 v2, v1, v2
	v_add_u32_e32 v1, v1, v2
	s_waitcnt vmcnt(0)
	v_mul_hi_u32 v1, v0, v1
	v_mul_lo_u32 v2, v1, v116
	v_add_u32_e32 v4, 1, v0
	v_sub_u32_e32 v0, v0, v2
	v_add_u32_e32 v3, 1, v1
	v_sub_u32_e32 v2, v0, v116
	v_cmp_ge_u32_e32 vcc, v0, v116
	s_nop 1
	v_cndmask_b32_e32 v1, v1, v3, vcc
	v_cndmask_b32_e32 v0, v0, v2, vcc
	v_add_u32_e32 v2, 1, v1
	v_cmp_ge_u32_e32 vcc, v0, v116
	s_nop 1
	v_cndmask_b32_e32 v0, v1, v2, vcc
	v_mad_u64_u32 v[2:3], s[4:5], v116, v0, v[116:117]
	v_cmp_ne_u32_e32 vcc, v4, v2
	s_and_saveexec_b64 s[4:5], vcc
	s_xor_b64 s[4:5], exec, s[4:5]
	s_cbranch_execz .LBB0_178
	v_readlane_b32 s16, v221, 3
	v_readlane_b32 s17, v221, 4
	s_nop 4
	global_load_dword v1, v96, s[16:17] sc1
	s_waitcnt vmcnt(0)
	v_cmp_eq_u32_e32 vcc, v1, v0
	s_and_saveexec_b64 s[38:39], vcc
	s_cbranch_execz .LBB0_177
	s_mov_b32 s15, 1
	s_mov_b64 s[42:43], 0
	s_branch .LBB0_168

; DI unsigned xb_ld(unsigned* p) { return __hip_atomic_load(p, __ATOMIC_RELAXED, __HIP_MEMORY_SCOPE_AGENT); }
; #define XB_SPIN(cond, bar) do { unsigned _sp = 0; while (cond) { __builtin_amdgcn_s_sleep(1); \
;     if ((++_sp & 255u) == 0u) { if (xb_ld(&(bar)[XB_TMO])) break; if (_sp > XB_SPIN_CAP) { atomicAdd(&(bar)[XB_TMO], 1u); break; } } } } while (0)
; DI void xcd_barrier(XcdBarrier& b) {
;     ...
;       XB_SPIN(xb_ld(&bar[XB_XGEN(b.x)]) == gen, bar);
;       __builtin_amdgcn_fence(__ATOMIC_ACQUIRE, "agent");
.LBB0_172:
	v_readlane_b32 s16, v221, 3
	v_readlane_b32 s17, v221, 4
	s_nop 4
	global_load_dword v1, v96, s[16:17] sc1
	s_add_i32 s15, s15, 1
	s_mov_b64 s[48:49], -1
	s_waitcnt vmcnt(0)
	v_cmp_ne_u32_e32 vcc, v1, v0
	s_orn2_b64 s[46:47], vcc, exec
	s_branch .LBB0_167

; DI unsigned xb_ld(unsigned* p) { return __hip_atomic_load(p, __ATOMIC_RELAXED, __HIP_MEMORY_SCOPE_AGENT); }
; DI unsigned xb_add(unsigned* p, unsigned v) { return __hip_atomic_fetch_add(p, v, __ATOMIC_RELAXED, __HIP_MEMORY_SCOPE_AGENT); }
; #define XB_SPIN(cond, bar) do { unsigned _sp = 0; while (cond) { __builtin_amdgcn_s_sleep(1); \
;     if ((++_sp & 255u) == 0u) { if (xb_ld(&(bar)[XB_TMO])) break; if (_sp > XB_SPIN_CAP) { atomicAdd(&(bar)[XB_TMO], 1u); break; } } } } while (0)
; DI void xcd_barrier(XcdBarrier& b) {
;     ...
;     const unsigned old = xb_add(&bar[XB_XSUB(b.x)], 1u);
;     const unsigned gen = old / nloc;
;     if (old + 1u == (gen + 1u) * nloc) {
;       __builtin_amdgcn_fence(__ATOMIC_RELEASE, "agent");
;       asm volatile("s_waitcnt vmcnt(0)" ::: "memory");
;       const unsigned og = xb_add(&bar[XB_TOP], 1u);
;       const unsigned tg = og / nx;
;       if (og + 1u == (tg + 1u) * nx) xb_add(&bar[XB_TOPGEN], 1u);
;       else XB_SPIN(xb_ld(&bar[XB_TOPGEN]) == tg, bar);
;       __builtin_amdgcn_fence(__ATOMIC_ACQUIRE, "agent");
;       xb_add(&bar[XB_XGEN(b.x)], 1u);
;       asm volatile("s_waitcnt vmcnt(0)" ::: "memory");
;     } else {
;       XB_SPIN(xb_ld(&bar[XB_XGEN(b.x)]) == gen, bar);
.LBB0_219:
	s_or_b64 exec, exec, s[4:5]
	global_atomic_add v1, v[110:111], v133, off sc0
	v_cvt_f32_u32_e32 v0, v116
	v_sub_u32_e32 v2, 0, v116
	v_rcp_iflag_f32_e32 v0, v0
	s_nop 0
	v_mul_f32_e32 v0, 0x4f7ffffe, v0
	v_cvt_u32_f32_e32 v0, v0
	v_mul_lo_u32 v2, v2, v0
	v_mul_hi_u32 v2, v0, v2
	v_add_u32_e32 v0, v0, v2
	s_waitcnt vmcnt(0)
	v_mul_hi_u32 v0, v1, v0
	v_mul_lo_u32 v2, v0, v116
	v_sub_u32_e32 v2, v1, v2
	v_cmp_ge_u32_e32 vcc, v2, v116
	v_add_u32_e32 v3, 1, v0
	v_add_u32_e32 v1, 1, v1
	v_cndmask_b32_e32 v0, v0, v3, vcc
	v_sub_u32_e32 v3, v2, v116
	v_cndmask_b32_e32 v2, v2, v3, vcc
	v_cmp_ge_u32_e32 vcc, v2, v116
	v_add_u32_e32 v2, 1, v0
	s_nop 0
	v_cndmask_b32_e32 v0, v0, v2, vcc
	v_mad_u64_u32 v[2:3], s[4:5], v116, v0, v[116:117]
	v_cmp_ne_u32_e32 vcc, v1, v2
	s_and_saveexec_b64 s[4:5], vcc
	s_xor_b64 s[4:5], exec, s[4:5]
	s_cbranch_execz .LBB0_233
	v_readlane_b32 s16, v221, 3
	v_readlane_b32 s17, v221, 4
	s_nop 4
	global_load_dword v1, v96, s[16:17] sc1
	s_waitcnt vmcnt(0)
	v_cmp_eq_u32_e32 vcc, v1, v0
	s_and_saveexec_b64 s[38:39], vcc
	s_cbranch_execz .LBB0_232
	s_mov_b32 s15, 1
	s_mov_b64 s[42:43], 0
	s_branch .LBB0_223

; DI unsigned xb_ld(unsigned* p) { return __hip_atomic_load(p, __ATOMIC_RELAXED, __HIP_MEMORY_SCOPE_AGENT); }
; DI unsigned xb_add(unsigned* p, unsigned v) { return __hip_atomic_fetch_add(p, v, __ATOMIC_RELAXED, __HIP_MEMORY_SCOPE_AGENT); }
; #define XB_SPIN(cond, bar) do { unsigned _sp = 0; while (cond) { __builtin_amdgcn_s_sleep(1); \
;     if ((++_sp & 255u) == 0u) { if (xb_ld(&(bar)[XB_TMO])) break; if (_sp > XB_SPIN_CAP) { atomicAdd(&(bar)[XB_TMO], 1u); break; } } } } while (0)
; DI void xcd_barrier(XcdBarrier& b) {
;     ...
;     const unsigned old = xb_add(&bar[XB_XSUB(b.x)], 1u);
;     const unsigned gen = old / nloc;
;     if (old + 1u == (gen + 1u) * nloc) {
;       __builtin_amdgcn_fence(__ATOMIC_RELEASE, "agent");
;       asm volatile("s_waitcnt vmcnt(0)" ::: "memory");
;       const unsigned og = xb_add(&bar[XB_TOP], 1u);
;       const unsigned tg = og / nx;
;       if (og + 1u == (tg + 1u) * nx) xb_add(&bar[XB_TOPGEN], 1u);
;       else XB_SPIN(xb_ld(&bar[XB_TOPGEN]) == tg, bar);
;       __builtin_amdgcn_fence(__ATOMIC_ACQUIRE, "agent");
;       xb_add(&bar[XB_XGEN(b.x)], 1u);
;       asm volatile("s_waitcnt vmcnt(0)" ::: "memory");
;     } else {
;       XB_SPIN(xb_ld(&bar[XB_XGEN(b.x)]) == gen, bar);
.LBB0_538:
	s_or_b64 exec, exec, s[4:5]
	global_atomic_add v1, v[110:111], v133, off sc0
	v_cvt_f32_u32_e32 v0, v116
	v_sub_u32_e32 v2, 0, v116
	v_rcp_iflag_f32_e32 v0, v0
	s_nop 0
	v_mul_f32_e32 v0, 0x4f7ffffe, v0
	v_cvt_u32_f32_e32 v0, v0
	v_mul_lo_u32 v2, v2, v0
	v_mul_hi_u32 v2, v0, v2
	v_add_u32_e32 v0, v0, v2
	s_waitcnt vmcnt(0)
	v_mul_hi_u32 v0, v1, v0
	v_mul_lo_u32 v2, v0, v116
	v_sub_u32_e32 v2, v1, v2
	v_cmp_ge_u32_e32 vcc, v2, v116
	v_add_u32_e32 v3, 1, v0
	v_add_u32_e32 v1, 1, v1
	v_cndmask_b32_e32 v0, v0, v3, vcc
	v_sub_u32_e32 v3, v2, v116
	v_cndmask_b32_e32 v2, v2, v3, vcc
	v_cmp_ge_u32_e32 vcc, v2, v116
	v_add_u32_e32 v2, 1, v0
	s_nop 0
	v_cndmask_b32_e32 v0, v0, v2, vcc
	v_mad_u64_u32 v[2:3], s[4:5], v116, v0, v[116:117]
	v_cmp_ne_u32_e32 vcc, v1, v2
	s_and_saveexec_b64 s[4:5], vcc
	s_xor_b64 s[4:5], exec, s[4:5]
	s_cbranch_execz .LBB0_552
	v_readlane_b32 s16, v221, 3
	v_readlane_b32 s17, v221, 4
	s_nop 4
	global_load_dword v1, v96, s[16:17] sc1
	s_waitcnt vmcnt(0)
	v_cmp_eq_u32_e32 vcc, v1, v0
	s_and_saveexec_b64 s[38:39], vcc
	s_cbranch_execz .LBB0_551
	s_mov_b32 s15, 1
	s_mov_b64 s[40:41], 0
	s_branch .LBB0_542

; DI unsigned xb_ld(unsigned* p) { return __hip_atomic_load(p, __ATOMIC_RELAXED, __HIP_MEMORY_SCOPE_AGENT); }
; #define XB_SPIN(cond, bar) do { unsigned _sp = 0; while (cond) { __builtin_amdgcn_s_sleep(1); \
;     if ((++_sp & 255u) == 0u) { if (xb_ld(&(bar)[XB_TMO])) break; if (_sp > XB_SPIN_CAP) { atomicAdd(&(bar)[XB_TMO], 1u); break; } } } } while (0)
; DI void xcd_barrier(XcdBarrier& b) {
;     ...
;       XB_SPIN(xb_ld(&bar[XB_XGEN(b.x)]) == gen, bar);
;       __builtin_amdgcn_fence(__ATOMIC_ACQUIRE, "agent");
.LBB0_546:
	v_readlane_b32 s16, v221, 3
	v_readlane_b32 s17, v221, 4
	s_nop 4
	global_load_dword v1, v96, s[16:17] sc1
	s_add_i32 s15, s15, 1
	s_mov_b64 s[46:47], -1
	s_waitcnt vmcnt(0)
	v_cmp_ne_u32_e32 vcc, v1, v0
	s_orn2_b64 s[44:45], vcc, exec
	s_branch .LBB0_541

; DI unsigned xb_ld(unsigned* p) { return __hip_atomic_load(p, __ATOMIC_RELAXED, __HIP_MEMORY_SCOPE_AGENT); }
; DI unsigned xb_add(unsigned* p, unsigned v) { return __hip_atomic_fetch_add(p, v, __ATOMIC_RELAXED, __HIP_MEMORY_SCOPE_AGENT); }
; #define XB_SPIN(cond, bar) do { unsigned _sp = 0; while (cond) { __builtin_amdgcn_s_sleep(1); \
;     if ((++_sp & 255u) == 0u) { if (xb_ld(&(bar)[XB_TMO])) break; if (_sp > XB_SPIN_CAP) { atomicAdd(&(bar)[XB_TMO], 1u); break; } } } } while (0)
; DI void xcd_barrier(XcdBarrier& b) {
;     ...
;     const unsigned old = xb_add(&bar[XB_XSUB(b.x)], 1u);
;     const unsigned gen = old / nloc;
;     if (old + 1u == (gen + 1u) * nloc) {
;       __builtin_amdgcn_fence(__ATOMIC_RELEASE, "agent");
;       asm volatile("s_waitcnt vmcnt(0)" ::: "memory");
;       const unsigned og = xb_add(&bar[XB_TOP], 1u);
;       const unsigned tg = og / nx;
;       if (og + 1u == (tg + 1u) * nx) xb_add(&bar[XB_TOPGEN], 1u);
;       else XB_SPIN(xb_ld(&bar[XB_TOPGEN]) == tg, bar);
;       __builtin_amdgcn_fence(__ATOMIC_ACQUIRE, "agent");
;       xb_add(&bar[XB_XGEN(b.x)], 1u);
;       asm volatile("s_waitcnt vmcnt(0)" ::: "memory");
;     } else {
;       XB_SPIN(xb_ld(&bar[XB_XGEN(b.x)]) == gen, bar);
.LBB0_675:
	s_or_b64 exec, exec, s[4:5]
	global_atomic_add v1, v[110:111], v133, off sc0
	v_cvt_f32_u32_e32 v0, v98
	v_sub_u32_e32 v2, 0, v98
	v_rcp_iflag_f32_e32 v0, v0
	s_nop 0
	v_mul_f32_e32 v0, 0x4f7ffffe, v0
	v_cvt_u32_f32_e32 v0, v0
	v_mul_lo_u32 v2, v2, v0
	v_mul_hi_u32 v2, v0, v2
	v_add_u32_e32 v0, v0, v2
	s_waitcnt vmcnt(0)
	v_mul_hi_u32 v0, v1, v0
	v_mul_lo_u32 v2, v0, v98
	v_sub_u32_e32 v2, v1, v2
	v_cmp_ge_u32_e32 vcc, v2, v98
	v_add_u32_e32 v3, 1, v0
	v_add_u32_e32 v1, 1, v1
	v_cndmask_b32_e32 v0, v0, v3, vcc
	v_sub_u32_e32 v3, v2, v98
	v_cndmask_b32_e32 v2, v2, v3, vcc
	v_cmp_ge_u32_e32 vcc, v2, v98
	v_add_u32_e32 v2, 1, v0
	s_nop 0
	v_cndmask_b32_e32 v0, v0, v2, vcc
	v_mad_u64_u32 v[2:3], s[4:5], v98, v0, v[98:99]
	v_cmp_ne_u32_e32 vcc, v1, v2
	s_and_saveexec_b64 s[4:5], vcc
	s_xor_b64 s[4:5], exec, s[4:5]
	s_cbranch_execz .LBB0_689
	v_readlane_b32 s16, v221, 3
	v_readlane_b32 s17, v221, 4
	s_nop 4
	global_load_dword v1, v96, s[16:17] sc1
	s_waitcnt vmcnt(0)
	v_cmp_eq_u32_e32 vcc, v1, v0
	s_and_saveexec_b64 s[38:39], vcc
	s_cbranch_execz .LBB0_688
	s_mov_b32 s15, 1
	s_mov_b64 s[40:41], 0
	s_branch .LBB0_679
